# phase 0 copy of x into the residual stream: four 16-byte loads in flight per thread
# speedup vs baseline: 1.0559x; 1.0010x over previous
.LBB0_718:
	s_andn2_b64 vcc, exec, s[46:47]
	v_readlane_b32 s28, v244, 17
	v_readlane_b32 s30, v244, 19
	v_readlane_b32 s36, v244, 21
	v_readlane_b32 s38, v244, 23
	v_readlane_b32 s40, v244, 25
	v_readlane_b32 s42, v244, 27
	v_readlane_b32 s44, v244, 29
	v_readlane_b32 s46, v244, 31
	v_readlane_b32 s29, v244, 18
	v_readlane_b32 s31, v244, 20
	v_readlane_b32 s37, v244, 22
	v_readlane_b32 s39, v244, 24
	v_readlane_b32 s41, v244, 26
	v_readlane_b32 s43, v244, 28
	v_readlane_b32 s45, v244, 30
	v_readlane_b32 s47, v244, 32
	s_cbranch_vccnz .LBB0_797
	v_readlane_b32 s4, v244, 34
	s_nop 1
	v_mov_b32_e32 v2, s4
	ds_read_b64 v[0:1], v2 offset:48
	ds_read_b32 v2, v2 offset:36
	s_waitcnt lgkmcnt(0)
	v_readfirstlane_b32 s1, v1
	v_cmp_ne_u32_e32 vcc, 1, v2
	v_readfirstlane_b32 s0, v0
	s_cbranch_vccnz .LBB0_727
	v_readlane_b32 s2, v246, 18
	v_ashrrev_i32_e32 v151, 31, v150
	v_readlane_b32 s3, v246, 19
	s_nop 1
	v_lshl_add_u64 v[0:1], s[2:3], 0, v[150:151]
	s_mov_b64 s[2:3], 0x400000
	v_cmp_gt_u64_e32 vcc, s[2:3], v[0:1]
	s_and_saveexec_b64 s[2:3], vcc
	v_readlane_b32 s10, v244, 10
	v_readlane_b32 s11, v244, 11
	s_cbranch_execz .LBB0_723
	v_readlane_b32 s4, v244, 34
	s_nop 1
	v_mov_b32_e32 v2, s4
	ds_read_b64 v[2:3], v2 offset:96
	v_readlane_b32 s4, v245, 3
	v_readlane_b32 s5, v245, 4
	s_nop 1
	v_lshl_add_u64 v[4:5], v[150:151], 4, s[4:5]
	s_mov_b64 s[4:5], 0
	s_cmp_lg_u32 s6, 0x100
	s_cbranch_scc1 .LBB0_722
	s_waitcnt lgkmcnt(0)
	s_lshl_b64 s[8:9], s[10:11], 2
	s_movk_i32 s4, 8
.Lp0cp_loop:
	v_lshl_add_u64 v[6:7], v[2:3], 0, v[4:5]
	v_lshl_add_u64 v[10:11], s[0:1], 0, v[4:5]
	global_load_dwordx4 v[12:15], v[6:7], off
	v_lshl_add_u64 v[6:7], v[6:7], 0, s[10:11]
	global_load_dwordx4 v[16:19], v[6:7], off
	v_lshl_add_u64 v[6:7], v[6:7], 0, s[10:11]
	global_load_dwordx4 v[20:23], v[6:7], off
	v_lshl_add_u64 v[6:7], v[6:7], 0, s[10:11]
	global_load_dwordx4 v[24:27], v[6:7], off
	s_waitcnt vmcnt(3)
	global_store_dwordx4 v[10:11], v[12:15], off
	v_lshl_add_u64 v[10:11], v[10:11], 0, s[10:11]
	s_waitcnt vmcnt(3)
	global_store_dwordx4 v[10:11], v[16:19], off
	v_lshl_add_u64 v[10:11], v[10:11], 0, s[10:11]
	s_waitcnt vmcnt(3)
	global_store_dwordx4 v[10:11], v[20:23], off
	v_lshl_add_u64 v[10:11], v[10:11], 0, s[10:11]
	s_waitcnt vmcnt(3)
	global_store_dwordx4 v[10:11], v[24:27], off
	v_lshl_add_u64 v[4:5], v[4:5], 0, s[8:9]
	s_add_i32 s4, s4, -1
	s_cmp_lg_u32 s4, 0
	s_cbranch_scc1 .Lp0cp_loop
	s_branch .LBB0_723
